# nt also on the read-once residual/base loads of the P7 and P10 EpiRes epilogues (on top of the norm-loop nt loads)
# speedup vs baseline: 1.0005x; 1.0005x over previous
.LBB0_1079:
	s_ashr_i32 s17, s16, 31
	s_lshl_b64 s[16:17], s[16:17], 19
	s_lshl_b64 s[22:23], s[28:29], 2
	v_mov_b32_e32 v146, v1
	v_lshl_or_b32 v122, s18, 8, v190
	s_add_u32 s22, s77, s22
	s_addc_u32 s23, s78, s23
	v_add_u32_e32 v150, v122, v146
	v_ashrrev_i32_e32 v151, 31, v150
	v_lshl_add_u64 v[126:127], v[150:151], 2, s[22:23]
	global_load_dwordx4 v[130:133], v[126:127], off offset:16
	global_load_dwordx4 v[134:137], v[126:127], off
	global_load_dwordx4 v[122:125], v[126:127], off offset:528
	s_nop 0
	global_load_dwordx4 v[126:129], v[126:127], off offset:512
	v_readlane_b32 s26, v255, 7
	s_add_u32 s22, s88, s16
	v_readlane_b32 s27, v255, 8
	s_addc_u32 s23, s89, s17
	v_add_u32_e32 v146, v146, v188
	s_andn2_b64 vcc, exec, s[26:27]
	v_readlane_b32 s26, v255, 0
	v_readlane_b32 s30, v255, 2
	s_mov_b64 s[16:17], -1
	v_ashrrev_i32_e32 v147, 31, v146
	v_lshl_add_u64 v[148:149], v[150:151], 1, s[22:23]
	v_readlane_b32 s27, v255, 1
	v_readlane_b32 s31, v255, 3
	s_cbranch_vccnz .LBB0_1081
	v_lshl_add_u64 v[150:151], v[150:151], 2, s[20:21]
	v_lshlrev_b64 v[152:153], 12, v[146:147]
	v_lshl_add_u64 v[164:165], v[150:151], 0, v[152:153]
	global_load_dwordx4 v[152:155], v[164:165], off offset:16 nt
	global_load_dwordx4 v[156:159], v[164:165], off nt
	global_load_dwordx4 v[160:163], v[164:165], off offset:528 nt
	global_load_dwordx4 v[176:179], v[164:165], off offset:512 nt
	v_add_u32_e32 v164, 16, v146
	v_ashrrev_i32_e32 v165, 31, v164
	v_lshlrev_b64 v[180:181], 12, v[164:165]
	v_lshl_add_u64 v[196:197], v[150:151], 0, v[180:181]
	global_load_dwordx4 v[180:183], v[196:197], off offset:16 nt
	global_load_dwordx4 v[184:187], v[196:197], off nt
	global_load_dwordx4 v[192:195], v[196:197], off offset:528 nt
	s_nop 0
	global_load_dwordx4 v[196:199], v[196:197], off offset:512 nt
	v_lshlrev_b64 v[200:201], 11, v[146:147]
	v_lshl_add_u64 v[200:201], v[148:149], 0, v[200:201]
	s_mov_b64 s[16:17], 0
	s_waitcnt vmcnt(0)
	v_pk_fma_f32 v[202:203], v[140:141], v[132:133], v[154:155]
	v_pk_fma_f32 v[158:159], v[144:145], v[136:137], v[158:159]
	v_pk_fma_f32 v[156:157], v[142:143], v[134:135], v[156:157]
	v_pk_fma_f32 v[154:155], v[138:139], v[130:131], v[152:153]
	v_cvt_pk_bf16_f32 v152, v156, v157
	v_cvt_pk_bf16_f32 v153, v158, v159
	v_pk_fma_f32 v[156:157], v[116:117], v[124:125], v[162:163]
	v_cvt_pk_bf16_f32 v154, v154, v155
	v_cvt_pk_bf16_f32 v155, v202, v203
	global_store_dwordx4 v[200:201], v[152:155], off
	v_pk_fma_f32 v[158:159], v[114:115], v[122:123], v[160:161]
	v_pk_fma_f32 v[160:161], v[106:107], v[130:131], v[180:181]
	v_pk_fma_f32 v[152:153], v[118:119], v[126:127], v[176:177]
	v_pk_fma_f32 v[154:155], v[120:121], v[128:129], v[178:179]
	v_cvt_pk_bf16_f32 v152, v152, v153
	s_nop 0
	v_cvt_pk_bf16_f32 v153, v154, v155
	v_cvt_pk_bf16_f32 v154, v158, v159
	v_cvt_pk_bf16_f32 v155, v156, v157
	global_store_dwordx4 v[200:201], v[152:155], off offset:256
	v_pk_fma_f32 v[158:159], v[108:109], v[132:133], v[182:183]
	v_add_u32_e32 v200, 48, v146
	v_lshlrev_b64 v[152:153], 11, v[164:165]
	v_lshl_add_u64 v[156:157], v[148:149], 0, v[152:153]
	v_pk_fma_f32 v[152:153], v[110:111], v[134:135], v[184:185]
	v_pk_fma_f32 v[154:155], v[112:113], v[136:137], v[186:187]
	v_cvt_pk_bf16_f32 v152, v152, v153
	v_add_u32_e32 v164, 32, v146
	v_cvt_pk_bf16_f32 v153, v154, v155
	v_cvt_pk_bf16_f32 v154, v160, v161
	v_cvt_pk_bf16_f32 v155, v158, v159
	global_store_dwordx4 v[156:157], v[152:155], off
	v_ashrrev_i32_e32 v165, 31, v164
	v_pk_fma_f32 v[158:159], v[100:101], v[124:125], v[194:195]
	v_pk_fma_f32 v[152:153], v[102:103], v[126:127], v[196:197]
	v_pk_fma_f32 v[154:155], v[104:105], v[128:129], v[198:199]
	v_cvt_pk_bf16_f32 v152, v152, v153
	v_pk_fma_f32 v[160:161], v[98:99], v[122:123], v[192:193]
	v_cvt_pk_bf16_f32 v153, v154, v155
	v_ashrrev_i32_e32 v201, 31, v200
	v_cvt_pk_bf16_f32 v154, v160, v161
	v_cvt_pk_bf16_f32 v155, v158, v159
	global_store_dwordx4 v[156:157], v[152:155], off offset:256
	v_lshlrev_b64 v[180:181], 12, v[200:201]
	v_lshl_add_u64 v[196:197], v[150:151], 0, v[180:181]
	v_lshlrev_b64 v[152:153], 12, v[164:165]
	v_lshl_add_u64 v[176:177], v[150:151], 0, v[152:153]
	global_load_dwordx4 v[152:155], v[176:177], off offset:16 nt
	global_load_dwordx4 v[156:159], v[176:177], off nt
	global_load_dwordx4 v[160:163], v[176:177], off offset:528 nt
	s_nop 0
	global_load_dwordx4 v[176:179], v[176:177], off offset:512 nt
	s_nop 0
	global_load_dwordx4 v[180:183], v[196:197], off offset:16 nt
	global_load_dwordx4 v[184:187], v[196:197], off nt
	global_load_dwordx4 v[192:195], v[196:197], off offset:528 nt
	s_nop 0
	global_load_dwordx4 v[196:199], v[196:197], off offset:512 nt
	v_lshlrev_b64 v[164:165], 11, v[164:165]
	v_lshl_add_u64 v[164:165], v[148:149], 0, v[164:165]
	s_waitcnt vmcnt(0)
	v_pk_fma_f32 v[202:203], v[92:93], v[132:133], v[154:155]
	v_pk_fma_f32 v[158:159], v[96:97], v[136:137], v[158:159]
	v_pk_fma_f32 v[156:157], v[94:95], v[134:135], v[156:157]
	v_pk_fma_f32 v[154:155], v[90:91], v[130:131], v[152:153]
	v_cvt_pk_bf16_f32 v152, v156, v157
	v_cvt_pk_bf16_f32 v153, v158, v159
	v_pk_fma_f32 v[156:157], v[84:85], v[124:125], v[162:163]
	v_cvt_pk_bf16_f32 v154, v154, v155
	v_cvt_pk_bf16_f32 v155, v202, v203
	global_store_dwordx4 v[164:165], v[152:155], off
	v_pk_fma_f32 v[158:159], v[82:83], v[122:123], v[160:161]
	v_pk_fma_f32 v[160:161], v[74:75], v[130:131], v[180:181]
	v_pk_fma_f32 v[152:153], v[86:87], v[126:127], v[176:177]
	v_pk_fma_f32 v[154:155], v[88:89], v[128:129], v[178:179]
	v_cvt_pk_bf16_f32 v152, v152, v153
	s_nop 0
	v_cvt_pk_bf16_f32 v153, v154, v155
	v_cvt_pk_bf16_f32 v154, v158, v159
	v_cvt_pk_bf16_f32 v155, v156, v157
	global_store_dwordx4 v[164:165], v[152:155], off offset:256
	v_pk_fma_f32 v[158:159], v[76:77], v[132:133], v[182:183]
	v_add_u32_e32 v164, 0x80, v146
	v_lshlrev_b64 v[152:153], 11, v[200:201]
	v_lshl_add_u64 v[156:157], v[148:149], 0, v[152:153]
	v_pk_fma_f32 v[152:153], v[78:79], v[134:135], v[184:185]
	v_pk_fma_f32 v[154:155], v[80:81], v[136:137], v[186:187]
	v_cvt_pk_bf16_f32 v152, v152, v153
	v_ashrrev_i32_e32 v165, 31, v164
	v_cvt_pk_bf16_f32 v153, v154, v155
	v_cvt_pk_bf16_f32 v154, v160, v161
	v_cvt_pk_bf16_f32 v155, v158, v159
	global_store_dwordx4 v[156:157], v[152:155], off
	v_pk_fma_f32 v[158:159], v[68:69], v[124:125], v[194:195]
	v_pk_fma_f32 v[160:161], v[66:67], v[122:123], v[192:193]
	v_pk_fma_f32 v[152:153], v[70:71], v[126:127], v[196:197]
	v_pk_fma_f32 v[154:155], v[72:73], v[128:129], v[198:199]
	v_cvt_pk_bf16_f32 v152, v152, v153
	v_add_u32_e32 v200, 0x90, v146
	v_cvt_pk_bf16_f32 v153, v154, v155
	v_cvt_pk_bf16_f32 v154, v160, v161
	v_cvt_pk_bf16_f32 v155, v158, v159
	global_store_dwordx4 v[156:157], v[152:155], off offset:256
	v_ashrrev_i32_e32 v201, 31, v200
	v_lshlrev_b64 v[180:181], 12, v[200:201]
	v_lshlrev_b64 v[152:153], 12, v[164:165]
	v_lshl_add_u64 v[176:177], v[150:151], 0, v[152:153]
	global_load_dwordx4 v[152:155], v[176:177], off offset:16 nt
	global_load_dwordx4 v[156:159], v[176:177], off nt
	global_load_dwordx4 v[160:163], v[176:177], off offset:528 nt
	s_nop 0
	global_load_dwordx4 v[176:179], v[176:177], off offset:512 nt
	v_lshl_add_u64 v[196:197], v[150:151], 0, v[180:181]
	global_load_dwordx4 v[180:183], v[196:197], off offset:16 nt
	global_load_dwordx4 v[184:187], v[196:197], off nt
	global_load_dwordx4 v[192:195], v[196:197], off offset:528 nt
	s_nop 0
	global_load_dwordx4 v[196:199], v[196:197], off offset:512 nt
	v_lshlrev_b64 v[164:165], 11, v[164:165]
	v_lshl_add_u64 v[164:165], v[148:149], 0, v[164:165]
	s_waitcnt vmcnt(0)
	v_pk_fma_f32 v[202:203], v[60:61], v[132:133], v[154:155]
	v_pk_fma_f32 v[158:159], v[64:65], v[136:137], v[158:159]
	v_pk_fma_f32 v[156:157], v[62:63], v[134:135], v[156:157]
	v_pk_fma_f32 v[154:155], v[58:59], v[130:131], v[152:153]
	v_cvt_pk_bf16_f32 v152, v156, v157
	v_cvt_pk_bf16_f32 v153, v158, v159
	v_pk_fma_f32 v[156:157], v[52:53], v[124:125], v[162:163]
	v_cvt_pk_bf16_f32 v154, v154, v155
	v_cvt_pk_bf16_f32 v155, v202, v203
	global_store_dwordx4 v[164:165], v[152:155], off
	v_pk_fma_f32 v[158:159], v[50:51], v[122:123], v[160:161]
	v_pk_fma_f32 v[160:161], v[42:43], v[130:131], v[180:181]
	v_pk_fma_f32 v[152:153], v[54:55], v[126:127], v[176:177]
	v_pk_fma_f32 v[154:155], v[56:57], v[128:129], v[178:179]
	v_cvt_pk_bf16_f32 v152, v152, v153
	s_nop 0
	v_cvt_pk_bf16_f32 v153, v154, v155
	v_cvt_pk_bf16_f32 v154, v158, v159
	v_cvt_pk_bf16_f32 v155, v156, v157
	global_store_dwordx4 v[164:165], v[152:155], off offset:256
	v_pk_fma_f32 v[158:159], v[44:45], v[132:133], v[182:183]
	v_add_u32_e32 v164, 0xa0, v146
	v_lshlrev_b64 v[152:153], 11, v[200:201]
	v_lshl_add_u64 v[156:157], v[148:149], 0, v[152:153]
	v_pk_fma_f32 v[152:153], v[46:47], v[134:135], v[184:185]
	v_pk_fma_f32 v[154:155], v[48:49], v[136:137], v[186:187]
	v_cvt_pk_bf16_f32 v152, v152, v153
	v_ashrrev_i32_e32 v165, 31, v164
	v_cvt_pk_bf16_f32 v153, v154, v155
	v_cvt_pk_bf16_f32 v154, v160, v161
	v_cvt_pk_bf16_f32 v155, v158, v159
	global_store_dwordx4 v[156:157], v[152:155], off
	v_pk_fma_f32 v[158:159], v[36:37], v[124:125], v[194:195]
	v_pk_fma_f32 v[160:161], v[34:35], v[122:123], v[192:193]
	v_pk_fma_f32 v[152:153], v[38:39], v[126:127], v[196:197]
	v_pk_fma_f32 v[154:155], v[40:41], v[128:129], v[198:199]
	v_cvt_pk_bf16_f32 v152, v152, v153
	v_add_u32_e32 v200, 0xb0, v146
	v_cvt_pk_bf16_f32 v153, v154, v155
	v_cvt_pk_bf16_f32 v154, v160, v161
	v_cvt_pk_bf16_f32 v155, v158, v159
	global_store_dwordx4 v[156:157], v[152:155], off offset:256
	v_ashrrev_i32_e32 v201, 31, v200
	v_lshlrev_b64 v[180:181], 12, v[200:201]
	v_lshlrev_b64 v[152:153], 12, v[164:165]
	v_lshl_add_u64 v[176:177], v[150:151], 0, v[152:153]
	global_load_dwordx4 v[152:155], v[176:177], off offset:16 nt
	global_load_dwordx4 v[156:159], v[176:177], off nt
	global_load_dwordx4 v[160:163], v[176:177], off offset:528 nt
	s_nop 0
	global_load_dwordx4 v[176:179], v[176:177], off offset:512 nt
	v_lshl_add_u64 v[150:151], v[150:151], 0, v[180:181]
	global_load_dwordx4 v[180:183], v[150:151], off offset:16 nt
	global_load_dwordx4 v[184:187], v[150:151], off nt
	global_load_dwordx4 v[192:195], v[150:151], off offset:528 nt
	global_load_dwordx4 v[196:199], v[150:151], off offset:512 nt
	v_lshlrev_b64 v[150:151], 11, v[164:165]
	v_lshl_add_u64 v[164:165], v[148:149], 0, v[150:151]
	s_waitcnt vmcnt(0)
	v_pk_fma_f32 v[152:153], v[26:27], v[130:131], v[152:153]
	v_pk_fma_f32 v[150:151], v[30:31], v[134:135], v[156:157]
	v_pk_fma_f32 v[158:159], v[32:33], v[136:137], v[158:159]
	v_cvt_pk_bf16_f32 v150, v150, v151
	v_pk_fma_f32 v[154:155], v[28:29], v[132:133], v[154:155]
	v_cvt_pk_bf16_f32 v151, v158, v159
	v_cvt_pk_bf16_f32 v152, v152, v153
	v_pk_fma_f32 v[156:157], v[18:19], v[122:123], v[160:161]
	v_cvt_pk_bf16_f32 v153, v154, v155
	global_store_dwordx4 v[164:165], v[150:153], off
	v_pk_fma_f32 v[154:155], v[20:21], v[124:125], v[162:163]
	v_pk_fma_f32 v[158:159], v[10:11], v[130:131], v[180:181]
	v_pk_fma_f32 v[150:151], v[22:23], v[126:127], v[176:177]
	v_pk_fma_f32 v[152:153], v[24:25], v[128:129], v[178:179]
	v_cvt_pk_bf16_f32 v150, v150, v151
	s_nop 0
	v_cvt_pk_bf16_f32 v151, v152, v153
	v_cvt_pk_bf16_f32 v152, v156, v157
	v_cvt_pk_bf16_f32 v153, v154, v155
	global_store_dwordx4 v[164:165], v[150:153], off offset:256
	v_pk_fma_f32 v[156:157], v[12:13], v[132:133], v[182:183]
	s_nop 0
	v_lshlrev_b64 v[150:151], 11, v[200:201]
	v_lshl_add_u64 v[154:155], v[148:149], 0, v[150:151]
	v_pk_fma_f32 v[152:153], v[16:17], v[136:137], v[186:187]
	v_pk_fma_f32 v[150:151], v[14:15], v[134:135], v[184:185]
	s_nop 0
	v_cvt_pk_bf16_f32 v150, v150, v151
	v_cvt_pk_bf16_f32 v151, v152, v153
	v_cvt_pk_bf16_f32 v152, v158, v159
	v_cvt_pk_bf16_f32 v153, v156, v157
	global_store_dwordx4 v[154:155], v[150:153], off
	v_pk_fma_f32 v[156:157], v[4:5], v[124:125], v[194:195]
	v_pk_fma_f32 v[158:159], v[2:3], v[122:123], v[192:193]
	v_pk_fma_f32 v[152:153], v[8:9], v[128:129], v[198:199]
	v_pk_fma_f32 v[150:151], v[6:7], v[126:127], v[196:197]
	s_nop 0
	v_cvt_pk_bf16_f32 v150, v150, v151
	v_cvt_pk_bf16_f32 v151, v152, v153
	v_cvt_pk_bf16_f32 v152, v158, v159
	v_cvt_pk_bf16_f32 v153, v156, v157
	global_store_dwordx4 v[154:155], v[150:153], off offset:256
.LBB0_1081:
	s_andn2_b64 vcc, exec, s[16:17]
	s_cbranch_vccnz .LBB0_1070
	v_lshlrev_b64 v[146:147], 11, v[146:147]
	v_lshl_add_u64 v[176:177], v[148:149], 0, v[146:147]
	global_load_dwordx4 v[192:195], v[176:177], off nt
	global_load_dwordx4 v[196:199], v[176:177], off offset:256 nt
	v_add_co_u32_e32 v204, vcc, 0x8000, v176
	s_mov_b64 s[16:17], 0x8000
	s_nop 0
	v_addc_co_u32_e32 v205, vcc, 0, v177, vcc
	v_lshl_add_u64 v[186:187], v[176:177], 0, s[16:17]
	global_load_dwordx4 v[200:203], v[204:205], off nt
	global_load_dwordx4 v[162:165], v[186:187], off offset:256 nt
	s_mov_b32 s7, 0x10000
	v_add_co_u32_e32 v184, vcc, s7, v176
	s_mov_b64 s[16:17], 0x10000
	s_nop 0
	v_addc_co_u32_e32 v185, vcc, 0, v177, vcc
	v_lshl_add_u64 v[182:183], v[176:177], 0, s[16:17]
	global_load_dwordx4 v[158:161], v[184:185], off nt
	global_load_dwordx4 v[154:157], v[182:183], off offset:256 nt
	s_mov_b32 s7, 0x18000
	v_add_co_u32_e32 v180, vcc, s7, v176
	s_mov_b64 s[16:17], 0x18000
	s_nop 0
	v_addc_co_u32_e32 v181, vcc, 0, v177, vcc
	v_lshl_add_u64 v[178:179], v[176:177], 0, s[16:17]
	global_load_dwordx4 v[150:153], v[180:181], off nt
	global_load_dwordx4 v[146:149], v[178:179], off offset:256 nt
	s_mov_b32 s7, 0x40000
	s_mov_b64 s[16:17], 0x48000
	s_waitcnt vmcnt(0)
	v_lshlrev_b32_e32 v206, 16, v192
	v_and_b32_e32 v207, 0xffff0000, v192
	v_lshlrev_b32_e32 v192, 16, v193
	v_and_b32_e32 v193, 0xffff0000, v193
	v_lshlrev_b32_e32 v208, 16, v194
	v_and_b32_e32 v209, 0xffff0000, v194
	v_lshlrev_b32_e32 v194, 16, v195
	v_and_b32_e32 v195, 0xffff0000, v195
	v_pk_fma_f32 v[144:145], v[144:145], v[136:137], v[192:193]
	v_pk_fma_f32 v[142:143], v[142:143], v[134:135], v[206:207]
	v_pk_fma_f32 v[192:193], v[140:141], v[132:133], v[194:195]
	v_pk_fma_f32 v[140:141], v[138:139], v[130:131], v[208:209]
	v_cvt_pk_bf16_f32 v138, v142, v143
	v_cvt_pk_bf16_f32 v139, v144, v145
	v_lshlrev_b32_e32 v142, 16, v198
	v_cvt_pk_bf16_f32 v140, v140, v141
	v_cvt_pk_bf16_f32 v141, v192, v193
	global_store_dwordx4 v[176:177], v[138:141], off
	v_and_b32_e32 v143, 0xffff0000, v198
	v_lshlrev_b32_e32 v144, 16, v199
	v_lshlrev_b32_e32 v138, 16, v196
	v_and_b32_e32 v139, 0xffff0000, v196
	v_and_b32_e32 v145, 0xffff0000, v199
	v_lshlrev_b32_e32 v140, 16, v197
	v_and_b32_e32 v141, 0xffff0000, v197
	v_pk_fma_f32 v[118:119], v[118:119], v[126:127], v[138:139]
	v_pk_fma_f32 v[138:139], v[116:117], v[124:125], v[144:145]
	v_pk_fma_f32 v[116:117], v[114:115], v[122:123], v[142:143]
	v_pk_fma_f32 v[120:121], v[120:121], v[128:129], v[140:141]
	v_cvt_pk_bf16_f32 v114, v118, v119
	v_lshlrev_b32_e32 v118, 16, v202
	v_cvt_pk_bf16_f32 v115, v120, v121
	v_cvt_pk_bf16_f32 v116, v116, v117
	v_cvt_pk_bf16_f32 v117, v138, v139
	global_store_dwordx4 v[176:177], v[114:117], off offset:256
	v_and_b32_e32 v119, 0xffff0000, v202
	v_lshlrev_b32_e32 v120, 16, v203
	v_lshlrev_b32_e32 v114, 16, v200
	v_and_b32_e32 v115, 0xffff0000, v200
	v_lshlrev_b32_e32 v116, 16, v201
	v_and_b32_e32 v117, 0xffff0000, v201
	v_and_b32_e32 v121, 0xffff0000, v203
	v_pk_fma_f32 v[112:113], v[112:113], v[136:137], v[116:117]
	v_pk_fma_f32 v[110:111], v[110:111], v[134:135], v[114:115]
	v_pk_fma_f32 v[114:115], v[108:109], v[132:133], v[120:121]
	v_pk_fma_f32 v[108:109], v[106:107], v[130:131], v[118:119]
	v_cvt_pk_bf16_f32 v106, v110, v111
	v_cvt_pk_bf16_f32 v107, v112, v113
	v_lshlrev_b32_e32 v110, 16, v164
	v_cvt_pk_bf16_f32 v108, v108, v109
	v_cvt_pk_bf16_f32 v109, v114, v115
	global_store_dwordx4 v[204:205], v[106:109], off
	v_and_b32_e32 v111, 0xffff0000, v164
	v_lshlrev_b32_e32 v112, 16, v165
	v_lshlrev_b32_e32 v106, 16, v162
	v_and_b32_e32 v107, 0xffff0000, v162
	v_and_b32_e32 v113, 0xffff0000, v165
	v_lshlrev_b32_e32 v108, 16, v163
	v_and_b32_e32 v109, 0xffff0000, v163
	v_pk_fma_f32 v[102:103], v[102:103], v[126:127], v[106:107]
	v_pk_fma_f32 v[106:107], v[100:101], v[124:125], v[112:113]
	v_pk_fma_f32 v[100:101], v[98:99], v[122:123], v[110:111]
	v_pk_fma_f32 v[104:105], v[104:105], v[128:129], v[108:109]
	v_cvt_pk_bf16_f32 v98, v102, v103
	v_lshlrev_b32_e32 v102, 16, v160
	v_cvt_pk_bf16_f32 v99, v104, v105
	v_cvt_pk_bf16_f32 v100, v100, v101
	v_cvt_pk_bf16_f32 v101, v106, v107
	global_store_dwordx4 v[186:187], v[98:101], off offset:256
	v_and_b32_e32 v103, 0xffff0000, v160
	v_lshlrev_b32_e32 v104, 16, v161
	v_lshlrev_b32_e32 v98, 16, v158
	v_and_b32_e32 v99, 0xffff0000, v158
	v_lshlrev_b32_e32 v100, 16, v159
	v_and_b32_e32 v101, 0xffff0000, v159
	v_and_b32_e32 v105, 0xffff0000, v161
	v_pk_fma_f32 v[96:97], v[96:97], v[136:137], v[100:101]
	v_pk_fma_f32 v[94:95], v[94:95], v[134:135], v[98:99]
	v_pk_fma_f32 v[98:99], v[92:93], v[132:133], v[104:105]
	v_pk_fma_f32 v[92:93], v[90:91], v[130:131], v[102:103]
	v_cvt_pk_bf16_f32 v90, v94, v95
	v_cvt_pk_bf16_f32 v91, v96, v97
	v_lshlrev_b32_e32 v94, 16, v156
	v_cvt_pk_bf16_f32 v92, v92, v93
	v_cvt_pk_bf16_f32 v93, v98, v99
	global_store_dwordx4 v[184:185], v[90:93], off
	v_and_b32_e32 v95, 0xffff0000, v156
	v_lshlrev_b32_e32 v96, 16, v157
	v_lshlrev_b32_e32 v90, 16, v154
	v_and_b32_e32 v91, 0xffff0000, v154
	v_and_b32_e32 v97, 0xffff0000, v157
	v_lshlrev_b32_e32 v92, 16, v155
	v_and_b32_e32 v93, 0xffff0000, v155
	v_pk_fma_f32 v[86:87], v[86:87], v[126:127], v[90:91]
	v_pk_fma_f32 v[90:91], v[84:85], v[124:125], v[96:97]
	v_pk_fma_f32 v[84:85], v[82:83], v[122:123], v[94:95]
	v_pk_fma_f32 v[88:89], v[88:89], v[128:129], v[92:93]
	v_cvt_pk_bf16_f32 v82, v86, v87
	v_lshlrev_b32_e32 v86, 16, v152
	v_cvt_pk_bf16_f32 v83, v88, v89
	v_cvt_pk_bf16_f32 v84, v84, v85
	v_cvt_pk_bf16_f32 v85, v90, v91
	global_store_dwordx4 v[182:183], v[82:85], off offset:256
	v_and_b32_e32 v87, 0xffff0000, v152
	v_lshlrev_b32_e32 v88, 16, v153
	v_lshlrev_b32_e32 v82, 16, v150
	v_and_b32_e32 v83, 0xffff0000, v150
	v_lshlrev_b32_e32 v84, 16, v151
	v_and_b32_e32 v85, 0xffff0000, v151
	v_and_b32_e32 v89, 0xffff0000, v153
	v_pk_fma_f32 v[80:81], v[80:81], v[136:137], v[84:85]
	v_pk_fma_f32 v[78:79], v[78:79], v[134:135], v[82:83]
	v_pk_fma_f32 v[82:83], v[76:77], v[132:133], v[88:89]
	v_pk_fma_f32 v[76:77], v[74:75], v[130:131], v[86:87]
	v_cvt_pk_bf16_f32 v74, v78, v79
	v_cvt_pk_bf16_f32 v75, v80, v81
	v_lshlrev_b32_e32 v78, 16, v148
	v_cvt_pk_bf16_f32 v76, v76, v77
	v_cvt_pk_bf16_f32 v77, v82, v83
	global_store_dwordx4 v[180:181], v[74:77], off
	v_and_b32_e32 v79, 0xffff0000, v148
	v_lshlrev_b32_e32 v80, 16, v149
	v_lshlrev_b32_e32 v74, 16, v146
	v_and_b32_e32 v75, 0xffff0000, v146
	v_and_b32_e32 v81, 0xffff0000, v149
	v_lshlrev_b32_e32 v76, 16, v147
	v_and_b32_e32 v77, 0xffff0000, v147
	v_pk_fma_f32 v[70:71], v[70:71], v[126:127], v[74:75]
	v_pk_fma_f32 v[74:75], v[68:69], v[124:125], v[80:81]
	v_pk_fma_f32 v[68:69], v[66:67], v[122:123], v[78:79]
	v_pk_fma_f32 v[72:73], v[72:73], v[128:129], v[76:77]
	v_cvt_pk_bf16_f32 v66, v70, v71
	v_add_co_u32_e32 v106, vcc, s7, v176
	v_cvt_pk_bf16_f32 v67, v72, v73
	v_cvt_pk_bf16_f32 v68, v68, v69
	v_cvt_pk_bf16_f32 v69, v74, v75
	global_store_dwordx4 v[178:179], v[66:69], off offset:256
	s_nop 0
	v_addc_co_u32_e32 v107, vcc, 0, v177, vcc
	v_lshl_add_u64 v[104:105], v[176:177], 0, s[2:3]
	global_load_dwordx4 v[80:83], v[106:107], off nt
	global_load_dwordx4 v[84:87], v[104:105], off offset:256 nt
	s_mov_b32 s7, 0x48000
	v_add_co_u32_e32 v110, vcc, s7, v176
	v_lshl_add_u64 v[108:109], v[176:177], 0, s[16:17]
	s_nop 0
	v_addc_co_u32_e32 v111, vcc, 0, v177, vcc
	global_load_dwordx4 v[88:91], v[110:111], off nt
	global_load_dwordx4 v[92:95], v[108:109], off offset:256 nt
	s_mov_b32 s7, 0x50000
	v_add_co_u32_e32 v112, vcc, s7, v176
	s_mov_b64 s[16:17], 0x50000
	s_nop 0
	v_addc_co_u32_e32 v113, vcc, 0, v177, vcc
	v_lshl_add_u64 v[78:79], v[176:177], 0, s[16:17]
	global_load_dwordx4 v[96:99], v[112:113], off nt
	global_load_dwordx4 v[100:103], v[78:79], off offset:256 nt
	s_mov_b32 s7, 0x58000
	v_add_co_u32_e32 v76, vcc, s7, v176
	s_mov_b64 s[16:17], 0x58000
	s_nop 0
	v_addc_co_u32_e32 v77, vcc, 0, v177, vcc
	v_lshl_add_u64 v[74:75], v[176:177], 0, s[16:17]
	global_load_dwordx4 v[70:73], v[76:77], off nt
	global_load_dwordx4 v[66:69], v[74:75], off offset:256 nt
	s_waitcnt vmcnt(0)
	v_lshlrev_b32_e32 v114, 16, v80
	v_and_b32_e32 v115, 0xffff0000, v80
	v_lshlrev_b32_e32 v80, 16, v81
	v_and_b32_e32 v81, 0xffff0000, v81
	v_lshlrev_b32_e32 v116, 16, v82
	v_and_b32_e32 v117, 0xffff0000, v82
	v_lshlrev_b32_e32 v82, 16, v83
	v_and_b32_e32 v83, 0xffff0000, v83
	v_pk_fma_f32 v[64:65], v[64:65], v[136:137], v[80:81]
	v_pk_fma_f32 v[62:63], v[62:63], v[134:135], v[114:115]
	v_pk_fma_f32 v[80:81], v[60:61], v[132:133], v[82:83]
	v_pk_fma_f32 v[60:61], v[58:59], v[130:131], v[116:117]
	v_cvt_pk_bf16_f32 v58, v62, v63
	v_cvt_pk_bf16_f32 v59, v64, v65
	v_lshlrev_b32_e32 v62, 16, v86
	v_cvt_pk_bf16_f32 v60, v60, v61
	v_cvt_pk_bf16_f32 v61, v80, v81
	global_store_dwordx4 v[106:107], v[58:61], off
	v_and_b32_e32 v63, 0xffff0000, v86
	v_lshlrev_b32_e32 v64, 16, v87
	v_lshlrev_b32_e32 v58, 16, v84
	v_and_b32_e32 v59, 0xffff0000, v84
	v_and_b32_e32 v65, 0xffff0000, v87
	v_lshlrev_b32_e32 v60, 16, v85
	v_and_b32_e32 v61, 0xffff0000, v85
	v_pk_fma_f32 v[54:55], v[54:55], v[126:127], v[58:59]
	v_pk_fma_f32 v[58:59], v[52:53], v[124:125], v[64:65]
	v_pk_fma_f32 v[52:53], v[50:51], v[122:123], v[62:63]
	v_pk_fma_f32 v[56:57], v[56:57], v[128:129], v[60:61]
	v_cvt_pk_bf16_f32 v50, v54, v55
	v_lshlrev_b32_e32 v54, 16, v90
	v_cvt_pk_bf16_f32 v51, v56, v57
	v_cvt_pk_bf16_f32 v52, v52, v53
	v_cvt_pk_bf16_f32 v53, v58, v59
	global_store_dwordx4 v[104:105], v[50:53], off offset:256
	v_and_b32_e32 v55, 0xffff0000, v90
	v_lshlrev_b32_e32 v56, 16, v91
	v_lshlrev_b32_e32 v50, 16, v88
	v_and_b32_e32 v51, 0xffff0000, v88
	v_lshlrev_b32_e32 v52, 16, v89
	v_and_b32_e32 v53, 0xffff0000, v89
	v_and_b32_e32 v57, 0xffff0000, v91
	v_pk_fma_f32 v[48:49], v[48:49], v[136:137], v[52:53]
	v_pk_fma_f32 v[46:47], v[46:47], v[134:135], v[50:51]
	v_pk_fma_f32 v[50:51], v[44:45], v[132:133], v[56:57]
	v_pk_fma_f32 v[44:45], v[42:43], v[130:131], v[54:55]
	v_cvt_pk_bf16_f32 v42, v46, v47
	v_cvt_pk_bf16_f32 v43, v48, v49
	v_lshlrev_b32_e32 v46, 16, v94
	v_cvt_pk_bf16_f32 v44, v44, v45
	v_cvt_pk_bf16_f32 v45, v50, v51
	global_store_dwordx4 v[110:111], v[42:45], off
	v_and_b32_e32 v47, 0xffff0000, v94
	v_lshlrev_b32_e32 v48, 16, v95
	v_lshlrev_b32_e32 v42, 16, v92
	v_and_b32_e32 v43, 0xffff0000, v92
	v_and_b32_e32 v49, 0xffff0000, v95
	v_lshlrev_b32_e32 v44, 16, v93
	v_and_b32_e32 v45, 0xffff0000, v93
	v_pk_fma_f32 v[38:39], v[38:39], v[126:127], v[42:43]
	v_pk_fma_f32 v[42:43], v[36:37], v[124:125], v[48:49]
	v_pk_fma_f32 v[36:37], v[34:35], v[122:123], v[46:47]
	v_pk_fma_f32 v[40:41], v[40:41], v[128:129], v[44:45]
	v_cvt_pk_bf16_f32 v34, v38, v39
	v_lshlrev_b32_e32 v38, 16, v98
	v_cvt_pk_bf16_f32 v35, v40, v41
	v_cvt_pk_bf16_f32 v36, v36, v37
	v_cvt_pk_bf16_f32 v37, v42, v43
	global_store_dwordx4 v[108:109], v[34:37], off offset:256
	v_and_b32_e32 v39, 0xffff0000, v98
	v_lshlrev_b32_e32 v40, 16, v99
	v_lshlrev_b32_e32 v34, 16, v96
	v_and_b32_e32 v35, 0xffff0000, v96
	v_lshlrev_b32_e32 v36, 16, v97
	v_and_b32_e32 v37, 0xffff0000, v97
	v_and_b32_e32 v41, 0xffff0000, v99
	v_pk_fma_f32 v[32:33], v[32:33], v[136:137], v[36:37]
	v_pk_fma_f32 v[30:31], v[30:31], v[134:135], v[34:35]
	v_pk_fma_f32 v[34:35], v[28:29], v[132:133], v[40:41]
	v_pk_fma_f32 v[28:29], v[26:27], v[130:131], v[38:39]
	v_cvt_pk_bf16_f32 v26, v30, v31
	v_cvt_pk_bf16_f32 v27, v32, v33
	v_lshlrev_b32_e32 v30, 16, v102
	v_cvt_pk_bf16_f32 v28, v28, v29
	v_cvt_pk_bf16_f32 v29, v34, v35
	global_store_dwordx4 v[112:113], v[26:29], off
	v_and_b32_e32 v31, 0xffff0000, v102
	v_lshlrev_b32_e32 v32, 16, v103
	v_lshlrev_b32_e32 v26, 16, v100
	v_and_b32_e32 v27, 0xffff0000, v100
	v_and_b32_e32 v33, 0xffff0000, v103
	v_lshlrev_b32_e32 v28, 16, v101
	v_and_b32_e32 v29, 0xffff0000, v101
	v_pk_fma_f32 v[22:23], v[22:23], v[126:127], v[26:27]
	v_pk_fma_f32 v[26:27], v[20:21], v[124:125], v[32:33]
	v_pk_fma_f32 v[20:21], v[18:19], v[122:123], v[30:31]
	v_pk_fma_f32 v[24:25], v[24:25], v[128:129], v[28:29]
	v_cvt_pk_bf16_f32 v18, v22, v23
	v_lshlrev_b32_e32 v22, 16, v72
	v_cvt_pk_bf16_f32 v19, v24, v25
	v_cvt_pk_bf16_f32 v20, v20, v21
	v_cvt_pk_bf16_f32 v21, v26, v27
	global_store_dwordx4 v[78:79], v[18:21], off offset:256
	v_and_b32_e32 v23, 0xffff0000, v72
	v_lshlrev_b32_e32 v24, 16, v73
	v_lshlrev_b32_e32 v18, 16, v70
	v_and_b32_e32 v19, 0xffff0000, v70
	v_lshlrev_b32_e32 v20, 16, v71
	v_and_b32_e32 v21, 0xffff0000, v71
	v_and_b32_e32 v25, 0xffff0000, v73
	v_pk_fma_f32 v[16:17], v[16:17], v[136:137], v[20:21]
	v_pk_fma_f32 v[14:15], v[14:15], v[134:135], v[18:19]
	v_pk_fma_f32 v[18:19], v[12:13], v[132:133], v[24:25]
	v_pk_fma_f32 v[12:13], v[10:11], v[130:131], v[22:23]
	v_cvt_pk_bf16_f32 v10, v14, v15
	v_cvt_pk_bf16_f32 v11, v16, v17
	v_lshlrev_b32_e32 v14, 16, v68
	v_cvt_pk_bf16_f32 v12, v12, v13
	v_cvt_pk_bf16_f32 v13, v18, v19
	global_store_dwordx4 v[76:77], v[10:13], off
	v_and_b32_e32 v15, 0xffff0000, v68
	v_lshlrev_b32_e32 v16, 16, v69
	v_lshlrev_b32_e32 v10, 16, v66
	v_and_b32_e32 v11, 0xffff0000, v66
	v_and_b32_e32 v17, 0xffff0000, v69
	v_lshlrev_b32_e32 v12, 16, v67
	v_and_b32_e32 v13, 0xffff0000, v67
	v_pk_fma_f32 v[6:7], v[6:7], v[126:127], v[10:11]
	v_pk_fma_f32 v[10:11], v[4:5], v[124:125], v[16:17]
	v_pk_fma_f32 v[4:5], v[2:3], v[122:123], v[14:15]
	v_pk_fma_f32 v[8:9], v[8:9], v[128:129], v[12:13]
	v_cvt_pk_bf16_f32 v2, v6, v7
	s_nop 0
	v_cvt_pk_bf16_f32 v3, v8, v9
	v_cvt_pk_bf16_f32 v4, v4, v5
	v_cvt_pk_bf16_f32 v5, v10, v11
	global_store_dwordx4 v[74:75], v[2:5], off offset:256
	s_branch .LBB0_1070

.LBB0_1269:
	s_ashr_i32 s13, s12, 31
	s_lshl_b64 s[12:13], s[12:13], 19
	s_lshl_b64 s[10:11], s[10:11], 2
	v_mov_b32_e32 v148, v1
	v_lshl_or_b32 v122, s76, 8, v192
	s_add_u32 s10, s35, s10
	s_addc_u32 s11, s61, s11
	v_add_u32_e32 v146, v122, v148
	v_ashrrev_i32_e32 v147, 31, v146
	v_lshl_add_u64 v[126:127], v[146:147], 2, s[10:11]
	s_add_u32 s10, s88, s12
	v_add_u32_e32 v148, v148, v190
	s_addc_u32 s11, s89, s13
	v_ashrrev_i32_e32 v149, 31, v148
	v_lshl_add_u64 v[146:147], v[146:147], 1, s[10:11]
	v_lshlrev_b64 v[148:149], 11, v[148:149]
	v_lshl_add_u64 v[176:177], v[146:147], 0, v[148:149]
	global_load_dwordx4 v[130:133], v[126:127], off offset:16
	global_load_dwordx4 v[134:137], v[126:127], off
	global_load_dwordx4 v[122:125], v[126:127], off offset:528
	s_nop 0
	global_load_dwordx4 v[126:129], v[126:127], off offset:512
	s_nop 0
	global_load_dwordx4 v[194:197], v[176:177], off nt
	global_load_dwordx4 v[198:201], v[176:177], off offset:256 nt
	v_add_co_u32_e32 v188, vcc, s53, v176
	v_lshl_add_u64 v[184:185], v[176:177], 0, s[68:69]
	s_nop 0
	v_addc_co_u32_e32 v189, vcc, 0, v177, vcc
	global_load_dwordx4 v[202:205], v[188:189], off nt
	global_load_dwordx4 v[162:165], v[184:185], off offset:256 nt
	s_mov_b32 s10, 0x10000
	v_add_co_u32_e32 v186, vcc, s10, v176
	v_lshl_add_u64 v[182:183], v[176:177], 0, s[70:71]
	s_nop 0
	v_addc_co_u32_e32 v187, vcc, 0, v177, vcc
	global_load_dwordx4 v[158:161], v[186:187], off nt
	global_load_dwordx4 v[154:157], v[182:183], off offset:256 nt
	v_add_co_u32_e32 v180, vcc, s52, v176
	v_lshl_add_u64 v[178:179], v[176:177], 0, s[72:73]
	s_nop 0
	v_addc_co_u32_e32 v181, vcc, 0, v177, vcc
	global_load_dwordx4 v[150:153], v[180:181], off nt
	global_load_dwordx4 v[146:149], v[178:179], off offset:256 nt
	s_mov_b32 s10, 0x40000
	s_mov_b32 s76, s65
	s_mov_b32 s12, s74
	s_mov_b64 s[16:17], s[8:9]
	s_mov_b64 s[14:15], s[6:7]
	s_waitcnt vmcnt(0)
	v_lshlrev_b32_e32 v206, 16, v194
	v_and_b32_e32 v207, 0xffff0000, v194
	v_lshlrev_b32_e32 v194, 16, v195
	v_and_b32_e32 v195, 0xffff0000, v195
	v_lshlrev_b32_e32 v208, 16, v196
	v_and_b32_e32 v209, 0xffff0000, v196
	v_lshlrev_b32_e32 v196, 16, v197
	v_and_b32_e32 v197, 0xffff0000, v197
	v_pk_fma_f32 v[144:145], v[144:145], v[136:137], v[194:195]
	v_pk_fma_f32 v[142:143], v[142:143], v[134:135], v[206:207]
	v_pk_fma_f32 v[194:195], v[140:141], v[132:133], v[196:197]
	v_pk_fma_f32 v[140:141], v[138:139], v[130:131], v[208:209]
	v_cvt_pk_bf16_f32 v138, v142, v143
	v_cvt_pk_bf16_f32 v139, v144, v145
	v_lshlrev_b32_e32 v142, 16, v200
	v_cvt_pk_bf16_f32 v140, v140, v141
	v_cvt_pk_bf16_f32 v141, v194, v195
	global_store_dwordx4 v[176:177], v[138:141], off
	v_and_b32_e32 v143, 0xffff0000, v200
	v_lshlrev_b32_e32 v144, 16, v201
	v_lshlrev_b32_e32 v138, 16, v198
	v_and_b32_e32 v139, 0xffff0000, v198
	v_and_b32_e32 v145, 0xffff0000, v201
	v_lshlrev_b32_e32 v140, 16, v199
	v_and_b32_e32 v141, 0xffff0000, v199
	v_pk_fma_f32 v[118:119], v[118:119], v[126:127], v[138:139]
	v_pk_fma_f32 v[138:139], v[116:117], v[124:125], v[144:145]
	v_pk_fma_f32 v[116:117], v[114:115], v[122:123], v[142:143]
	v_pk_fma_f32 v[120:121], v[120:121], v[128:129], v[140:141]
	v_cvt_pk_bf16_f32 v114, v118, v119
	v_lshlrev_b32_e32 v118, 16, v204
	v_cvt_pk_bf16_f32 v115, v120, v121
	v_cvt_pk_bf16_f32 v116, v116, v117
	v_cvt_pk_bf16_f32 v117, v138, v139
	global_store_dwordx4 v[176:177], v[114:117], off offset:256
	v_and_b32_e32 v119, 0xffff0000, v204
	v_lshlrev_b32_e32 v120, 16, v205
	v_lshlrev_b32_e32 v114, 16, v202
	v_and_b32_e32 v115, 0xffff0000, v202
	v_lshlrev_b32_e32 v116, 16, v203
	v_and_b32_e32 v117, 0xffff0000, v203
	v_and_b32_e32 v121, 0xffff0000, v205
	v_pk_fma_f32 v[112:113], v[112:113], v[136:137], v[116:117]
	v_pk_fma_f32 v[110:111], v[110:111], v[134:135], v[114:115]
	v_pk_fma_f32 v[114:115], v[108:109], v[132:133], v[120:121]
	v_pk_fma_f32 v[108:109], v[106:107], v[130:131], v[118:119]
	v_cvt_pk_bf16_f32 v106, v110, v111
	v_cvt_pk_bf16_f32 v107, v112, v113
	v_lshlrev_b32_e32 v110, 16, v164
	v_cvt_pk_bf16_f32 v108, v108, v109
	v_cvt_pk_bf16_f32 v109, v114, v115
	global_store_dwordx4 v[188:189], v[106:109], off
	v_and_b32_e32 v111, 0xffff0000, v164
	v_lshlrev_b32_e32 v112, 16, v165
	v_lshlrev_b32_e32 v106, 16, v162
	v_and_b32_e32 v107, 0xffff0000, v162
	v_and_b32_e32 v113, 0xffff0000, v165
	v_lshlrev_b32_e32 v108, 16, v163
	v_and_b32_e32 v109, 0xffff0000, v163
	v_pk_fma_f32 v[102:103], v[102:103], v[126:127], v[106:107]
	v_pk_fma_f32 v[106:107], v[100:101], v[124:125], v[112:113]
	v_pk_fma_f32 v[100:101], v[98:99], v[122:123], v[110:111]
	v_pk_fma_f32 v[104:105], v[104:105], v[128:129], v[108:109]
	v_cvt_pk_bf16_f32 v98, v102, v103
	v_lshlrev_b32_e32 v102, 16, v160
	v_cvt_pk_bf16_f32 v99, v104, v105
	v_cvt_pk_bf16_f32 v100, v100, v101
	v_cvt_pk_bf16_f32 v101, v106, v107
	global_store_dwordx4 v[184:185], v[98:101], off offset:256
	v_and_b32_e32 v103, 0xffff0000, v160
	v_lshlrev_b32_e32 v104, 16, v161
	v_lshlrev_b32_e32 v98, 16, v158
	v_and_b32_e32 v99, 0xffff0000, v158
	v_lshlrev_b32_e32 v100, 16, v159
	v_and_b32_e32 v101, 0xffff0000, v159
	v_and_b32_e32 v105, 0xffff0000, v161
	v_pk_fma_f32 v[96:97], v[96:97], v[136:137], v[100:101]
	v_pk_fma_f32 v[94:95], v[94:95], v[134:135], v[98:99]
	v_pk_fma_f32 v[98:99], v[92:93], v[132:133], v[104:105]
	v_pk_fma_f32 v[92:93], v[90:91], v[130:131], v[102:103]
	v_cvt_pk_bf16_f32 v90, v94, v95
	v_cvt_pk_bf16_f32 v91, v96, v97
	v_lshlrev_b32_e32 v94, 16, v156
	v_cvt_pk_bf16_f32 v92, v92, v93
	v_cvt_pk_bf16_f32 v93, v98, v99
	global_store_dwordx4 v[186:187], v[90:93], off
	v_and_b32_e32 v95, 0xffff0000, v156
	v_lshlrev_b32_e32 v96, 16, v157
	v_lshlrev_b32_e32 v90, 16, v154
	v_and_b32_e32 v91, 0xffff0000, v154
	v_and_b32_e32 v97, 0xffff0000, v157
	v_lshlrev_b32_e32 v92, 16, v155
	v_and_b32_e32 v93, 0xffff0000, v155
	v_pk_fma_f32 v[86:87], v[86:87], v[126:127], v[90:91]
	v_pk_fma_f32 v[90:91], v[84:85], v[124:125], v[96:97]
	v_pk_fma_f32 v[84:85], v[82:83], v[122:123], v[94:95]
	v_pk_fma_f32 v[88:89], v[88:89], v[128:129], v[92:93]
	v_cvt_pk_bf16_f32 v82, v86, v87
	v_lshlrev_b32_e32 v86, 16, v152
	v_cvt_pk_bf16_f32 v83, v88, v89
	v_cvt_pk_bf16_f32 v84, v84, v85
	v_cvt_pk_bf16_f32 v85, v90, v91
	global_store_dwordx4 v[182:183], v[82:85], off offset:256
	v_and_b32_e32 v87, 0xffff0000, v152
	v_lshlrev_b32_e32 v88, 16, v153
	v_lshlrev_b32_e32 v82, 16, v150
	v_and_b32_e32 v83, 0xffff0000, v150
	v_lshlrev_b32_e32 v84, 16, v151
	v_and_b32_e32 v85, 0xffff0000, v151
	v_and_b32_e32 v89, 0xffff0000, v153
	v_pk_fma_f32 v[80:81], v[80:81], v[136:137], v[84:85]
	v_pk_fma_f32 v[78:79], v[78:79], v[134:135], v[82:83]
	v_pk_fma_f32 v[82:83], v[76:77], v[132:133], v[88:89]
	v_pk_fma_f32 v[76:77], v[74:75], v[130:131], v[86:87]
	v_cvt_pk_bf16_f32 v74, v78, v79
	v_cvt_pk_bf16_f32 v75, v80, v81
	v_lshlrev_b32_e32 v78, 16, v148
	v_cvt_pk_bf16_f32 v76, v76, v77
	v_cvt_pk_bf16_f32 v77, v82, v83
	global_store_dwordx4 v[180:181], v[74:77], off
	v_and_b32_e32 v79, 0xffff0000, v148
	v_lshlrev_b32_e32 v80, 16, v149
	v_lshlrev_b32_e32 v74, 16, v146
	v_and_b32_e32 v75, 0xffff0000, v146
	v_and_b32_e32 v81, 0xffff0000, v149
	v_lshlrev_b32_e32 v76, 16, v147
	v_and_b32_e32 v77, 0xffff0000, v147
	v_pk_fma_f32 v[70:71], v[70:71], v[126:127], v[74:75]
	v_pk_fma_f32 v[74:75], v[68:69], v[124:125], v[80:81]
	v_pk_fma_f32 v[68:69], v[66:67], v[122:123], v[78:79]
	v_pk_fma_f32 v[72:73], v[72:73], v[128:129], v[76:77]
	v_cvt_pk_bf16_f32 v66, v70, v71
	v_add_co_u32_e32 v106, vcc, s10, v176
	v_cvt_pk_bf16_f32 v67, v72, v73
	v_cvt_pk_bf16_f32 v68, v68, v69
	v_cvt_pk_bf16_f32 v69, v74, v75
	global_store_dwordx4 v[178:179], v[66:69], off offset:256
	s_nop 0
	v_addc_co_u32_e32 v107, vcc, 0, v177, vcc
	v_lshl_add_u64 v[104:105], v[176:177], 0, s[2:3]
	global_load_dwordx4 v[80:83], v[106:107], off nt
	global_load_dwordx4 v[84:87], v[104:105], off offset:256 nt
	v_add_co_u32_e32 v110, vcc, s54, v176
	s_mov_b64 s[10:11], 0x48000
	s_nop 0
	v_addc_co_u32_e32 v111, vcc, 0, v177, vcc
	v_lshl_add_u64 v[108:109], v[176:177], 0, s[10:11]
	global_load_dwordx4 v[88:91], v[110:111], off nt
	global_load_dwordx4 v[92:95], v[108:109], off offset:256 nt
	s_mov_b64 s[10:11], 0x50000
	v_lshl_add_u64 v[78:79], v[176:177], 0, s[10:11]
	s_mov_b32 s10, 0x50000
	v_add_co_u32_e32 v112, vcc, s10, v176
	s_mov_b64 s[10:11], 0x58000
	s_nop 0
	v_addc_co_u32_e32 v113, vcc, 0, v177, vcc
	global_load_dwordx4 v[96:99], v[112:113], off nt
	global_load_dwordx4 v[100:103], v[78:79], off offset:256 nt
	v_add_co_u32_e32 v76, vcc, s66, v176
	v_lshl_add_u64 v[74:75], v[176:177], 0, s[10:11]
	s_nop 0
	v_addc_co_u32_e32 v77, vcc, 0, v177, vcc
	global_load_dwordx4 v[70:73], v[76:77], off nt
	global_load_dwordx4 v[66:69], v[74:75], off offset:256 nt
	s_and_b64 vcc, exec, s[0:1]
	s_waitcnt vmcnt(0)
	v_lshlrev_b32_e32 v114, 16, v80
	v_and_b32_e32 v115, 0xffff0000, v80
	v_lshlrev_b32_e32 v80, 16, v81
	v_and_b32_e32 v81, 0xffff0000, v81
	v_lshlrev_b32_e32 v116, 16, v82
	v_and_b32_e32 v117, 0xffff0000, v82
	v_lshlrev_b32_e32 v82, 16, v83
	v_and_b32_e32 v83, 0xffff0000, v83
	v_pk_fma_f32 v[64:65], v[64:65], v[136:137], v[80:81]
	v_pk_fma_f32 v[62:63], v[62:63], v[134:135], v[114:115]
	v_pk_fma_f32 v[80:81], v[60:61], v[132:133], v[82:83]
	v_pk_fma_f32 v[60:61], v[58:59], v[130:131], v[116:117]
	v_cvt_pk_bf16_f32 v58, v62, v63
	v_cvt_pk_bf16_f32 v59, v64, v65
	v_lshlrev_b32_e32 v62, 16, v86
	v_cvt_pk_bf16_f32 v60, v60, v61
	v_cvt_pk_bf16_f32 v61, v80, v81
	global_store_dwordx4 v[106:107], v[58:61], off
	v_and_b32_e32 v63, 0xffff0000, v86
	v_lshlrev_b32_e32 v64, 16, v87
	v_lshlrev_b32_e32 v58, 16, v84
	v_and_b32_e32 v59, 0xffff0000, v84
	v_and_b32_e32 v65, 0xffff0000, v87
	v_lshlrev_b32_e32 v60, 16, v85
	v_and_b32_e32 v61, 0xffff0000, v85
	v_pk_fma_f32 v[54:55], v[54:55], v[126:127], v[58:59]
	v_pk_fma_f32 v[58:59], v[52:53], v[124:125], v[64:65]
	v_pk_fma_f32 v[52:53], v[50:51], v[122:123], v[62:63]
	v_pk_fma_f32 v[56:57], v[56:57], v[128:129], v[60:61]
	v_cvt_pk_bf16_f32 v50, v54, v55
	v_lshlrev_b32_e32 v54, 16, v90
	v_cvt_pk_bf16_f32 v51, v56, v57
	v_cvt_pk_bf16_f32 v52, v52, v53
	v_cvt_pk_bf16_f32 v53, v58, v59
	global_store_dwordx4 v[104:105], v[50:53], off offset:256
	v_and_b32_e32 v55, 0xffff0000, v90
	v_lshlrev_b32_e32 v56, 16, v91
	v_lshlrev_b32_e32 v50, 16, v88
	v_and_b32_e32 v51, 0xffff0000, v88
	v_lshlrev_b32_e32 v52, 16, v89
	v_and_b32_e32 v53, 0xffff0000, v89
	v_and_b32_e32 v57, 0xffff0000, v91
	v_pk_fma_f32 v[48:49], v[48:49], v[136:137], v[52:53]
	v_pk_fma_f32 v[46:47], v[46:47], v[134:135], v[50:51]
	v_pk_fma_f32 v[50:51], v[44:45], v[132:133], v[56:57]
	v_pk_fma_f32 v[44:45], v[42:43], v[130:131], v[54:55]
	v_cvt_pk_bf16_f32 v42, v46, v47
	v_cvt_pk_bf16_f32 v43, v48, v49
	v_lshlrev_b32_e32 v46, 16, v94
	v_cvt_pk_bf16_f32 v44, v44, v45
	v_cvt_pk_bf16_f32 v45, v50, v51
	global_store_dwordx4 v[110:111], v[42:45], off
	v_and_b32_e32 v47, 0xffff0000, v94
	v_lshlrev_b32_e32 v48, 16, v95
	v_lshlrev_b32_e32 v42, 16, v92
	v_and_b32_e32 v43, 0xffff0000, v92
	v_and_b32_e32 v49, 0xffff0000, v95
	v_lshlrev_b32_e32 v44, 16, v93
	v_and_b32_e32 v45, 0xffff0000, v93
	v_pk_fma_f32 v[38:39], v[38:39], v[126:127], v[42:43]
	v_pk_fma_f32 v[42:43], v[36:37], v[124:125], v[48:49]
	v_pk_fma_f32 v[36:37], v[34:35], v[122:123], v[46:47]
	v_pk_fma_f32 v[40:41], v[40:41], v[128:129], v[44:45]
	v_cvt_pk_bf16_f32 v34, v38, v39
	v_lshlrev_b32_e32 v38, 16, v98
	v_cvt_pk_bf16_f32 v35, v40, v41
	v_cvt_pk_bf16_f32 v36, v36, v37
	v_cvt_pk_bf16_f32 v37, v42, v43
	global_store_dwordx4 v[108:109], v[34:37], off offset:256
	v_and_b32_e32 v39, 0xffff0000, v98
	v_lshlrev_b32_e32 v40, 16, v99
	v_lshlrev_b32_e32 v34, 16, v96
	v_and_b32_e32 v35, 0xffff0000, v96
	v_lshlrev_b32_e32 v36, 16, v97
	v_and_b32_e32 v37, 0xffff0000, v97
	v_and_b32_e32 v41, 0xffff0000, v99
	v_pk_fma_f32 v[32:33], v[32:33], v[136:137], v[36:37]
	v_pk_fma_f32 v[30:31], v[30:31], v[134:135], v[34:35]
	v_pk_fma_f32 v[34:35], v[28:29], v[132:133], v[40:41]
	v_pk_fma_f32 v[28:29], v[26:27], v[130:131], v[38:39]
	v_cvt_pk_bf16_f32 v26, v30, v31
	v_cvt_pk_bf16_f32 v27, v32, v33
	v_lshlrev_b32_e32 v30, 16, v102
	v_cvt_pk_bf16_f32 v28, v28, v29
	v_cvt_pk_bf16_f32 v29, v34, v35
	global_store_dwordx4 v[112:113], v[26:29], off
	v_and_b32_e32 v31, 0xffff0000, v102
	v_lshlrev_b32_e32 v32, 16, v103
	v_lshlrev_b32_e32 v26, 16, v100
	v_and_b32_e32 v27, 0xffff0000, v100
	v_and_b32_e32 v33, 0xffff0000, v103
	v_lshlrev_b32_e32 v28, 16, v101
	v_and_b32_e32 v29, 0xffff0000, v101
	v_pk_fma_f32 v[22:23], v[22:23], v[126:127], v[26:27]
	v_pk_fma_f32 v[26:27], v[20:21], v[124:125], v[32:33]
	v_pk_fma_f32 v[20:21], v[18:19], v[122:123], v[30:31]
	v_pk_fma_f32 v[24:25], v[24:25], v[128:129], v[28:29]
	v_cvt_pk_bf16_f32 v18, v22, v23
	v_lshlrev_b32_e32 v22, 16, v72
	v_cvt_pk_bf16_f32 v19, v24, v25
	v_cvt_pk_bf16_f32 v20, v20, v21
	v_cvt_pk_bf16_f32 v21, v26, v27
	global_store_dwordx4 v[78:79], v[18:21], off offset:256
	v_and_b32_e32 v23, 0xffff0000, v72
	v_lshlrev_b32_e32 v24, 16, v73
	v_lshlrev_b32_e32 v18, 16, v70
	v_and_b32_e32 v19, 0xffff0000, v70
	v_lshlrev_b32_e32 v20, 16, v71
	v_and_b32_e32 v21, 0xffff0000, v71
	v_and_b32_e32 v25, 0xffff0000, v73
	v_pk_fma_f32 v[16:17], v[16:17], v[136:137], v[20:21]
	v_pk_fma_f32 v[14:15], v[14:15], v[134:135], v[18:19]
	v_pk_fma_f32 v[18:19], v[12:13], v[132:133], v[24:25]
	v_pk_fma_f32 v[12:13], v[10:11], v[130:131], v[22:23]
	v_cvt_pk_bf16_f32 v10, v14, v15
	v_cvt_pk_bf16_f32 v11, v16, v17
	v_lshlrev_b32_e32 v14, 16, v68
	v_cvt_pk_bf16_f32 v12, v12, v13
	v_cvt_pk_bf16_f32 v13, v18, v19
	global_store_dwordx4 v[76:77], v[10:13], off
	v_and_b32_e32 v15, 0xffff0000, v68
	v_lshlrev_b32_e32 v16, 16, v69
	v_lshlrev_b32_e32 v10, 16, v66
	v_and_b32_e32 v11, 0xffff0000, v66
	v_and_b32_e32 v17, 0xffff0000, v69
	v_lshlrev_b32_e32 v12, 16, v67
	v_and_b32_e32 v13, 0xffff0000, v67
	v_pk_fma_f32 v[6:7], v[6:7], v[126:127], v[10:11]
	v_pk_fma_f32 v[10:11], v[4:5], v[124:125], v[16:17]
	v_pk_fma_f32 v[4:5], v[2:3], v[122:123], v[14:15]
	v_pk_fma_f32 v[8:9], v[8:9], v[128:129], v[12:13]
	v_cvt_pk_bf16_f32 v2, v6, v7
	s_nop 0
	v_cvt_pk_bf16_f32 v3, v8, v9
	v_cvt_pk_bf16_f32 v4, v4, v5
	v_cvt_pk_bf16_f32 v5, v10, v11
	global_store_dwordx4 v[74:75], v[2:5], off offset:256
	s_cbranch_vccnz .LBB0_1281
